# more instruction warm-up points: 64 KiB forward at every GEMM-part exit (copy / scan / barrier code) and 32 KiB at kernel entry, stacked on v93
# baseline (speedup 1.0000x reference)
_Z6mk_fwd4Args:
	s_load_dwordx8 s[4:11], s[0:1], 0xc0
	s_load_dword s54, s[0:1], 0xf8
	s_load_dwordx4 s[68:71], s[0:1], 0xe0
	s_load_dwordx2 s[52:53], s[0:1], 0xf0
	s_load_dword s72, s[0:1], 0x0
	s_load_dword s73, s[0:1], 0x40
	s_load_dword s74, s[0:1], 0x80
	s_load_dword s75, s[0:1], 0x100
	s_mov_b32 s56, s2
	v_readfirstlane_b32 s2, v0
	s_mov_b32 s33, s56
	s_lshr_b32 s98, s2, 6
	s_cmp_lg_u32 s98, 1
	s_cbranch_scc1 .Lcpf_skip_e
	s_getpc_b64 s[98:99]
.Lcpf_pc_e:
	s_add_u32 s98, s98, .Lcpf_pc_e-.Lcpf_pc_e
	s_addc_u32 s99, s99, 0
	v_and_b32_e32 v252, 63, v0
	v_lshlrev_b32_e32 v252, 7, v252
	global_load_dword v253, v252, s[98:99]
	s_add_u32 s98, s98, 0x2000
	s_addc_u32 s99, s99, 0
	global_load_dword v253, v252, s[98:99]
	s_add_u32 s98, s98, 0x2000
	s_addc_u32 s99, s99, 0
	global_load_dword v253, v252, s[98:99]
	s_add_u32 s98, s98, 0x2000
	s_addc_u32 s99, s99, 0
	global_load_dword v253, v252, s[98:99]
.Lcpf_skip_e:
	s_waitcnt lgkmcnt(0)
	v_writelane_b32 v254, s4, 0
	s_nop 1
	v_writelane_b32 v254, s5, 1
	v_writelane_b32 v254, s6, 2
	v_writelane_b32 v254, s7, 3
	v_writelane_b32 v254, s8, 4
	v_writelane_b32 v254, s9, 5
	v_writelane_b32 v254, s10, 6
	v_writelane_b32 v254, s11, 7
	s_add_u32 s4, s0, 0xf8
	s_addc_u32 s5, s1, 0
	v_writelane_b32 v254, s4, 8
	s_and_b32 s3, s54, 7
	s_cmp_lg_u32 s3, 0
	v_writelane_b32 v254, s5, 9
	s_cbranch_scc0 .LBB0_101
	v_cmp_gt_u32_e64 s[6:7], 64, v0
	s_and_saveexec_b64 s[4:5], s[6:7]

.LBB0_212:
	v_readlane_b32 s98, v254, 61
	s_cmp_lg_u32 s98, 1
	s_cbranch_scc1 .Lcpf_skip_g0
	s_getpc_b64 s[98:99]
.Lcpf_pc_g0:
	s_add_u32 s98, s98, .Lcpf_pc_g0-.Lcpf_pc_g0
	s_addc_u32 s99, s99, 0
	v_lshlrev_b32_e32 v252, 7, v186
	global_load_dword v253, v252, s[98:99]
	s_add_u32 s98, s98, 0x2000
	s_addc_u32 s99, s99, 0
	global_load_dword v253, v252, s[98:99]
	s_add_u32 s98, s98, 0x2000
	s_addc_u32 s99, s99, 0
	global_load_dword v253, v252, s[98:99]
	s_add_u32 s98, s98, 0x2000
	s_addc_u32 s99, s99, 0
	global_load_dword v253, v252, s[98:99]
	s_add_u32 s98, s98, 0x2000
	s_addc_u32 s99, s99, 0
	global_load_dword v253, v252, s[98:99]
	s_add_u32 s98, s98, 0x2000
	s_addc_u32 s99, s99, 0
	global_load_dword v253, v252, s[98:99]
	s_add_u32 s98, s98, 0x2000
	s_addc_u32 s99, s99, 0
	global_load_dword v253, v252, s[98:99]
	s_add_u32 s98, s98, 0x2000
	s_addc_u32 s99, s99, 0
	global_load_dword v253, v252, s[98:99]
.Lcpf_skip_g0:
	s_waitcnt vmcnt(0)
	v_readlane_b32 s52, v255, 7
	v_readlane_b32 s58, v255, 11
	v_readlane_b32 s97, v255, 4
	v_readlane_b32 s54, v255, 5
	v_readlane_b32 s56, v255, 6
	v_readlane_b32 s53, v255, 8
	v_readlane_b32 s57, v255, 9
	v_readlane_b32 s33, v255, 10
	v_readlane_b32 s59, v255, 12
	s_barrier

.Lcpf_pc_g1:
	s_add_u32 s98, s98, .Lcpf_pc_g1-.Lcpf_pc_g1
	s_addc_u32 s99, s99, 0
	v_lshlrev_b32_e32 v252, 7, v186
	global_load_dword v253, v252, s[98:99]
	s_add_u32 s98, s98, 0x2000
	s_addc_u32 s99, s99, 0
	global_load_dword v253, v252, s[98:99]
	s_add_u32 s98, s98, 0x2000
	s_addc_u32 s99, s99, 0
	global_load_dword v253, v252, s[98:99]
	s_add_u32 s98, s98, 0x2000
	s_addc_u32 s99, s99, 0
	global_load_dword v253, v252, s[98:99]
	s_add_u32 s98, s98, 0x2000
	s_addc_u32 s99, s99, 0
	global_load_dword v253, v252, s[98:99]
	s_add_u32 s98, s98, 0x2000
	s_addc_u32 s99, s99, 0
	global_load_dword v253, v252, s[98:99]
	s_add_u32 s98, s98, 0x2000
	s_addc_u32 s99, s99, 0
	global_load_dword v253, v252, s[98:99]
	s_add_u32 s98, s98, 0x2000
	s_addc_u32 s99, s99, 0
	global_load_dword v253, v252, s[98:99]
.Lcpf_skip_g1:
	s_waitcnt vmcnt(0)
	v_readlane_b32 s52, v255, 7
	v_readlane_b32 s58, v255, 11
	v_readlane_b32 s16, v255, 27
	v_readlane_b32 s56, v255, 6
	v_readlane_b32 s53, v255, 8
	v_readlane_b32 s57, v255, 9
	v_readlane_b32 s59, v255, 12
	v_readlane_b32 s17, v255, 28
	s_barrier

.Lcpf_pc_g2:
	s_add_u32 s98, s98, .Lcpf_pc_g2-.Lcpf_pc_g2
	s_addc_u32 s99, s99, 0
	v_lshlrev_b32_e32 v252, 7, v186
	global_load_dword v253, v252, s[98:99]
	s_add_u32 s98, s98, 0x2000
	s_addc_u32 s99, s99, 0
	global_load_dword v253, v252, s[98:99]
	s_add_u32 s98, s98, 0x2000
	s_addc_u32 s99, s99, 0
	global_load_dword v253, v252, s[98:99]
	s_add_u32 s98, s98, 0x2000
	s_addc_u32 s99, s99, 0
	global_load_dword v253, v252, s[98:99]
	s_add_u32 s98, s98, 0x2000
	s_addc_u32 s99, s99, 0
	global_load_dword v253, v252, s[98:99]
	s_add_u32 s98, s98, 0x2000
	s_addc_u32 s99, s99, 0
	global_load_dword v253, v252, s[98:99]
	s_add_u32 s98, s98, 0x2000
	s_addc_u32 s99, s99, 0
	global_load_dword v253, v252, s[98:99]
	s_add_u32 s98, s98, 0x2000
	s_addc_u32 s99, s99, 0
	global_load_dword v253, v252, s[98:99]
.Lcpf_skip_g2:
	s_waitcnt vmcnt(0)
	v_readlane_b32 s52, v255, 7
	v_readlane_b32 s36, v255, 33
	v_readlane_b32 s97, v255, 4
	v_readlane_b32 s56, v255, 6
	v_readlane_b32 s53, v255, 8
	v_readlane_b32 s57, v255, 9
	v_readlane_b32 s33, v255, 10
	v_readlane_b32 s37, v255, 34
	s_barrier

.Lcpf_pc_g3:
	s_add_u32 s98, s98, .Lcpf_pc_g3-.Lcpf_pc_g3
	s_addc_u32 s99, s99, 0
	v_lshlrev_b32_e32 v252, 7, v186
	global_load_dword v253, v252, s[98:99]
	s_add_u32 s98, s98, 0x2000
	s_addc_u32 s99, s99, 0
	global_load_dword v253, v252, s[98:99]
	s_add_u32 s98, s98, 0x2000
	s_addc_u32 s99, s99, 0
	global_load_dword v253, v252, s[98:99]
	s_add_u32 s98, s98, 0x2000
	s_addc_u32 s99, s99, 0
	global_load_dword v253, v252, s[98:99]
	s_add_u32 s98, s98, 0x2000
	s_addc_u32 s99, s99, 0
	global_load_dword v253, v252, s[98:99]
	s_add_u32 s98, s98, 0x2000
	s_addc_u32 s99, s99, 0
	global_load_dword v253, v252, s[98:99]
	s_add_u32 s98, s98, 0x2000
	s_addc_u32 s99, s99, 0
	global_load_dword v253, v252, s[98:99]
	s_add_u32 s98, s98, 0x2000
	s_addc_u32 s99, s99, 0
	global_load_dword v253, v252, s[98:99]
.Lcpf_skip_g3:
	s_waitcnt vmcnt(0)
	v_readlane_b32 s44, v255, 48
	v_readlane_b32 s88, v255, 11
	v_readlane_b32 s97, v255, 4
	v_readlane_b32 s56, v255, 6
	v_readlane_b32 s57, v255, 9
	v_readlane_b32 s33, v255, 10
	v_readlane_b32 s36, v255, 27
	v_readlane_b32 s45, v255, 49
	v_readlane_b32 s89, v255, 12
	s_barrier

.Lcpf_pc_g4:
	s_add_u32 s98, s98, .Lcpf_pc_g4-.Lcpf_pc_g4
	s_addc_u32 s99, s99, 0
	v_lshlrev_b32_e32 v252, 7, v186
	global_load_dword v253, v252, s[98:99]
	s_add_u32 s98, s98, 0x2000
	s_addc_u32 s99, s99, 0
	global_load_dword v253, v252, s[98:99]
	s_add_u32 s98, s98, 0x2000
	s_addc_u32 s99, s99, 0
	global_load_dword v253, v252, s[98:99]
	s_add_u32 s98, s98, 0x2000
	s_addc_u32 s99, s99, 0
	global_load_dword v253, v252, s[98:99]
	s_add_u32 s98, s98, 0x2000
	s_addc_u32 s99, s99, 0
	global_load_dword v253, v252, s[98:99]
	s_add_u32 s98, s98, 0x2000
	s_addc_u32 s99, s99, 0
	global_load_dword v253, v252, s[98:99]
	s_add_u32 s98, s98, 0x2000
	s_addc_u32 s99, s99, 0
	global_load_dword v253, v252, s[98:99]
	s_add_u32 s98, s98, 0x2000
	s_addc_u32 s99, s99, 0
	global_load_dword v253, v252, s[98:99]
.Lcpf_skip_g4:
	s_waitcnt vmcnt(0)
	v_readlane_b32 s20, v255, 50
	v_readlane_b32 s97, v255, 4
	v_readlane_b32 s54, v255, 5
	v_readlane_b32 s56, v255, 6
	v_readlane_b32 s57, v255, 9
	v_readlane_b32 s21, v255, 51
	s_barrier

.Lcpf_pc_g5:
	s_add_u32 s98, s98, .Lcpf_pc_g5-.Lcpf_pc_g5
	s_addc_u32 s99, s99, 0
	v_lshlrev_b32_e32 v252, 7, v186
	global_load_dword v253, v252, s[98:99]
	s_add_u32 s98, s98, 0x2000
	s_addc_u32 s99, s99, 0
	global_load_dword v253, v252, s[98:99]
	s_add_u32 s98, s98, 0x2000
	s_addc_u32 s99, s99, 0
	global_load_dword v253, v252, s[98:99]
	s_add_u32 s98, s98, 0x2000
	s_addc_u32 s99, s99, 0
	global_load_dword v253, v252, s[98:99]
	s_add_u32 s98, s98, 0x2000
	s_addc_u32 s99, s99, 0
	global_load_dword v253, v252, s[98:99]
	s_add_u32 s98, s98, 0x2000
	s_addc_u32 s99, s99, 0
	global_load_dword v253, v252, s[98:99]
	s_add_u32 s98, s98, 0x2000
	s_addc_u32 s99, s99, 0
	global_load_dword v253, v252, s[98:99]
	s_add_u32 s98, s98, 0x2000
	s_addc_u32 s99, s99, 0
	global_load_dword v253, v252, s[98:99]
.Lcpf_skip_g5:
	s_waitcnt vmcnt(0)
	v_readlane_b32 s36, v255, 44
	v_readlane_b32 s97, v255, 4
	v_readlane_b32 s54, v255, 5
	v_readlane_b32 s56, v255, 6
	v_readlane_b32 s57, v255, 9
	v_readlane_b32 s20, v255, 42
	v_readlane_b32 s37, v255, 45
	s_barrier

.Lcpf_pc_g6:
	s_add_u32 s98, s98, .Lcpf_pc_g6-.Lcpf_pc_g6
	s_addc_u32 s99, s99, 0
	v_lshlrev_b32_e32 v252, 7, v186
	global_load_dword v253, v252, s[98:99]
	s_add_u32 s98, s98, 0x2000
	s_addc_u32 s99, s99, 0
	global_load_dword v253, v252, s[98:99]
	s_add_u32 s98, s98, 0x2000
	s_addc_u32 s99, s99, 0
	global_load_dword v253, v252, s[98:99]
	s_add_u32 s98, s98, 0x2000
	s_addc_u32 s99, s99, 0
	global_load_dword v253, v252, s[98:99]
	s_add_u32 s98, s98, 0x2000
	s_addc_u32 s99, s99, 0
	global_load_dword v253, v252, s[98:99]
	s_add_u32 s98, s98, 0x2000
	s_addc_u32 s99, s99, 0
	global_load_dword v253, v252, s[98:99]
	s_add_u32 s98, s98, 0x2000
	s_addc_u32 s99, s99, 0
	global_load_dword v253, v252, s[98:99]
	s_add_u32 s98, s98, 0x2000
	s_addc_u32 s99, s99, 0
	global_load_dword v253, v252, s[98:99]
.Lcpf_skip_g6:
	s_waitcnt vmcnt(0)
	v_readlane_b32 s36, v255, 7
	v_readlane_b32 s97, v255, 4
	v_readlane_b32 s54, v255, 5
	v_readlane_b32 s56, v255, 6
	v_readlane_b32 s37, v255, 8
	v_readlane_b32 s57, v255, 9
	s_mov_b64 s[48:49], s[22:23]
	v_readlane_b32 s0, v255, 23
	s_barrier
